# baseline (speedup 1.0000x reference)
; __device__ __forceinline__ void finishSM(f32x16& p0, f32x16& p1, float alpha, float& l_reg, bf16x8& pa0, bf16x8& pa1, bf16x8& pa2, bf16x8& pa3) {
; #pragma unroll
;   for (int r = 0; r < 16; ++r) p1[r] = __builtin_amdgcn_exp2f(p1[r]);
;   float ps = 0;
; #pragma unroll
;   for (int r = 0; r < 16; ++r) ps += p0[r];
; #pragma unroll
;   for (int r = 0; r < 16; ++r) ps += p1[r];
;   { auto rr = __builtin_amdgcn_permlane32_swap(__float_as_uint(ps), __float_as_uint(ps), false, false);
;     ps = __uint_as_float(rr[0]) + __uint_as_float(rr[1]); }
;   l_reg = l_reg * alpha + ps;
;     ...
;   PK4(p0, 0, pa0); PK4(p0, 8, pa1); PK4(p1, 0, pa2); PK4(p1, 8, pa3);
; template <int BUFOFF>
; __device__ __forceinline__ void qkt_mla(f32x16& p0, f32x16& p1, const int* ka, const bf16x8* qr, const char* qlds) {
;   typedef __attribute__((address_space(3))) const bf16x8* lp;
;   p0 = f32x16{}; p1 = f32x16{};
; #pragma unroll
;   for (int d0 = 0; d0 < 12; ++d0) {
;     const int a = ka[d0 & 3] + (d0 >> 2) * 128 + BUFOFF;
;     const bf16x8 b0 = *(lp)(a), b1 = *(lp)(a + 12288);
;     bf16x8 qf;
;     qf = qr[d0];
;     p0 = __builtin_amdgcn_mfma_f32_32x32x16_bf16(b0, qf, p0, 0, 0, 0);
;     p1 = __builtin_amdgcn_mfma_f32_32x32x16_bf16(b1, qf, p1, 0, 0, 0);
;   }
; }
.LBB0_115:
	s_mov_b32 s55, s43
	s_mov_b32 s43, s52
	ds_read_b128 v[64:67], v169 offset:24576
	ds_read_b128 v[68:71], v169 offset:36864
	ds_read_b128 v[214:217], v190 offset:24576
	ds_read_b128 v[218:221], v190 offset:36864
	s_waitcnt lgkmcnt(0)
	v_mfma_f32_32x32x16_bf16 v[80:95], v[64:67], v[140:143], v[226:241]
	v_add_f32_e32 v144, v200, v145
	v_mfma_f32_32x32x16_bf16 v[64:79], v[68:71], v[140:143], v[226:241]
	v_add_f32_e32 v243, v203, v210
	v_add_f32_e32 v244, v202, v208
	v_add_f32_e32 v245, v205, v212
	v_add_f32_e32 v246, v199, v211
	v_add_f32_e32 v247, v201, v213
	v_mfma_f32_32x32x16_bf16 v[80:95], v[214:217], v[136:139], v[80:95]
	v_add_f32_e32 v251, v204, v207
	v_add_f32_e32 v252, v206, v209
	v_mov_b32_e32 v196, v158
	v_add_f32_e32 v144, v172, v144
	v_add_f32_e32 v243, v173, v243
	v_mfma_f32_32x32x16_bf16 v[64:79], v[218:221], v[136:139], v[64:79]
	ds_read_b128 v[214:217], v193 offset:24576
	ds_read_b128 v[218:221], v193 offset:36864
	v_add_f32_e32 v244, v170, v244
	v_add_f32_e32 v245, v171, v245
	v_add_f32_e32 v246, v196, v246
	v_mov_b32_e32 v222, v147
	v_mov_b32_e32 v223, v154
	v_mov_b32_e32 v224, v155
	s_waitcnt lgkmcnt(0)
	v_mfma_f32_32x32x16_bf16 v[80:95], v[214:217], v[132:135], v[80:95]
	v_mfma_f32_32x32x16_bf16 v[64:79], v[218:221], v[132:135], v[64:79]
	ds_read_b128 v[214:217], v192 offset:24576
	ds_read_b128 v[218:221], v192 offset:36864
	s_waitcnt lgkmcnt(0)
	v_mfma_f32_32x32x16_bf16 v[80:95], v[214:217], v[128:131], v[80:95]
	v_mfma_f32_32x32x16_bf16 v[64:79], v[218:221], v[128:131], v[64:79]
	ds_read_b128 v[214:217], v169 offset:24704
	ds_read_b128 v[218:221], v169 offset:36992
	s_waitcnt lgkmcnt(0)
	v_mfma_f32_32x32x16_bf16 v[80:95], v[214:217], v[124:127], v[80:95]
	v_mfma_f32_32x32x16_bf16 v[64:79], v[218:221], v[124:127], v[64:79]
	ds_read_b128 v[214:217], v190 offset:24704
	ds_read_b128 v[218:221], v190 offset:36992
	s_waitcnt lgkmcnt(0)
	v_mfma_f32_32x32x16_bf16 v[80:95], v[214:217], v[120:123], v[80:95]
	v_mfma_f32_32x32x16_bf16 v[64:79], v[218:221], v[120:123], v[64:79]
	ds_read_b128 v[214:217], v193 offset:24704
	ds_read_b128 v[218:221], v193 offset:36992
	s_waitcnt lgkmcnt(0)
	v_mfma_f32_32x32x16_bf16 v[80:95], v[214:217], v[116:119], v[80:95]
	v_mfma_f32_32x32x16_bf16 v[64:79], v[218:221], v[116:119], v[64:79]
	ds_read_b128 v[214:217], v192 offset:24704
	ds_read_b128 v[218:221], v192 offset:36992
	s_waitcnt lgkmcnt(0)
	v_mfma_f32_32x32x16_bf16 v[80:95], v[214:217], v[112:115], v[80:95]
	v_mfma_f32_32x32x16_bf16 v[64:79], v[218:221], v[112:115], v[64:79]
	ds_read_b128 v[214:217], v169 offset:24832
	ds_read_b128 v[218:221], v169 offset:37120
	s_waitcnt lgkmcnt(0)
	v_mfma_f32_32x32x16_bf16 v[80:95], v[214:217], v[108:111], v[80:95]
	v_mfma_f32_32x32x16_bf16 v[64:79], v[218:221], v[108:111], v[64:79]
	ds_read_b128 v[214:217], v190 offset:24832
	ds_read_b128 v[218:221], v190 offset:37120
	s_waitcnt lgkmcnt(0)
	v_mfma_f32_32x32x16_bf16 v[80:95], v[214:217], v[104:107], v[80:95]
	v_mfma_f32_32x32x16_bf16 v[64:79], v[218:221], v[104:107], v[64:79]
	ds_read_b128 v[214:217], v193 offset:24832
	ds_read_b128 v[218:221], v193 offset:37120
	s_waitcnt lgkmcnt(0)
	v_mfma_f32_32x32x16_bf16 v[80:95], v[214:217], v[100:103], v[80:95]
	v_mfma_f32_32x32x16_bf16 v[64:79], v[218:221], v[100:103], v[64:79]
	ds_read_b128 v[214:217], v192 offset:24832
	ds_read_b128 v[218:221], v192 offset:37120
	s_waitcnt lgkmcnt(0)
	v_mfma_f32_32x32x16_bf16 v[80:95], v[214:217], v[96:99], v[80:95]
	v_mov_b32_e32 v214, v159
	v_mov_b32_e32 v215, v152
	v_mov_b32_e32 v216, v153
	v_mov_b32_e32 v217, v150
	v_add_f32_e32 v247, v214, v247
	v_add_f32_e32 v251, v215, v251
	v_add_f32_e32 v252, v216, v252
	v_mfma_f32_32x32x16_bf16 v[64:79], v[218:221], v[96:99], v[64:79]
	v_mov_b32_e32 v218, v151
	v_mov_b32_e32 v219, v148
	v_mov_b32_e32 v220, v149
	v_mov_b32_e32 v221, v146
	v_add_f32_e32 v144, v217, v144
	v_add_f32_e32 v243, v218, v243
	v_add_f32_e32 v244, v219, v244
	v_add_f32_e32 v245, v220, v245
	v_add_f32_e32 v246, v221, v246
	v_add_f32_e32 v247, v222, v247
	v_add_f32_e32 v251, v223, v251
	v_add_f32_e32 v252, v224, v252
	v_add_f32_e32 v144, v144, v243
	v_add_f32_e32 v244, v244, v245
	v_add_f32_e32 v246, v246, v247
	v_add_f32_e32 v251, v251, v252
	v_add_f32_e32 v144, v144, v244
	v_add_f32_e32 v246, v246, v251
	v_add_f32_e32 v158, v144, v246
	v_mov_b32_e32 v159, v158
	v_cvt_pk_bf16_f32 v144, v145, v210
	v_cvt_pk_bf16_f32 v145, v208, v212
	v_cvt_pk_bf16_f32 v146, v211, v213
	v_cvt_pk_bf16_f32 v147, v207, v209
	v_cvt_pk_bf16_f32 v148, v200, v203
	v_cvt_pk_bf16_f32 v149, v202, v205
	v_cvt_pk_bf16_f32 v150, v199, v201
	v_cvt_pk_bf16_f32 v151, v204, v206
	v_cvt_pk_bf16_f32 v152, v172, v173
	v_cvt_pk_bf16_f32 v153, v170, v171
	v_cvt_pk_bf16_f32 v154, v196, v214
	s_nop 1
	v_permlane32_swap_b32_e32 v158, v159
	v_cvt_pk_bf16_f32 v155, v215, v216
	v_cvt_pk_bf16_f32 v170, v217, v218
	v_cvt_pk_bf16_f32 v171, v219, v220
	v_cvt_pk_bf16_f32 v172, v221, v222
	v_cvt_pk_bf16_f32 v173, v223, v224
	v_readlane_b32 s58, v249, 37
	v_readlane_b32 s59, v249, 38
	s_add_u32 s56, s58, s47
	s_addc_u32 s57, s59, s50
	s_add_u32 s4, s56, 0x17060000
	s_addc_u32 s5, s57, 0
	s_add_u32 s58, s58, s14
	s_addc_u32 s59, s59, s15
	s_add_u32 s60, s58, 0x1a040000
	s_mov_b32 m0, s41
	s_addc_u32 s61, s59, 0
	s_lshl_b32 s52, s54, 14
	s_add_i32 s62, s40, s52
	global_load_lds_dwordx4 v188, s[4:5]
	s_mov_b32 m0, s42
	s_nop 0
	global_load_lds_dwordx4 v189, s[4:5]
	s_add_i32 m0, s41, 0x4000
	s_nop 0
	global_load_lds_dwordx4 v191, s[4:5]
	s_mov_b32 m0, s62
	s_nop 0
	global_load_lds_dwordx4 v194, s[60:61]
	s_add_i32 m0, s62, 0x2000
	s_nop 0
	global_load_lds_dwordx4 v195, s[60:61]
	s_lshl_b32 s60, s43, 14
	v_add_u32_e32 v196, s60, v167
	ds_read_b64_tr_b16 v[200:201], v196 offset:0
	ds_read_b64_tr_b16 v[202:203], v196 offset:0x800
	ds_read_b64_tr_b16 v[204:205], v196 offset:0x1000
	ds_read_b64_tr_b16 v[206:207], v196 offset:0x1800
	ds_read_b64_tr_b16 v[208:209], v196 offset:0x2000
	ds_read_b64_tr_b16 v[210:211], v196 offset:0x2800
	ds_read_b64_tr_b16 v[212:213], v196 offset:0x3000
	ds_read_b64_tr_b16 v[214:215], v196 offset:0x3800
	s_nop 0
	s_waitcnt lgkmcnt(6)
; #define SBAR() __builtin_amdgcn_sched_barrier(0)
; template <int MLA>
; __device__ __forceinline__ void partialSM(f32x16& p0, f32x16& p1, float& m_reg, float& mn, float& alpha) {
;     ...
;   float pmax = p0[0];
; #pragma unroll
;   for (int r = 1; r < 16; ++r) pmax = fmaxf(pmax, p0[r]);
; #pragma unroll
;   for (int r = 0; r < 16; ++r) pmax = fmaxf(pmax, p1[r]);
;   { auto rr = __builtin_amdgcn_permlane32_swap(__float_as_uint(pmax), __float_as_uint(pmax), false, false);
;     pmax = fmaxf(__uint_as_float(rr[0]), __uint_as_float(rr[1])); }
;   if (__builtin_expect(__all(pmax - m_reg <= THR / SCALE), 1)) { mn = m_reg; alpha = 1.f; }
;   else { mn = fmaxf(m_reg, pmax); alpha = __builtin_amdgcn_exp2f((m_reg - mn) * C); m_reg = mn; }
;   float mnC = -mn * C;
; #pragma unroll
;   for (int r = 0; r < 16; ++r) p0[r] = fmaf(p0[r], C, mnC);
; #pragma unroll
;   for (int r = 0; r < 16; ++r) p1[r] = fmaf(p1[r], C, mnC);
; template <int D0> __device__ __forceinline__ void pv_one_t(f32x16& od, int vb, bf16x8 pa0, bf16x8 pa1, bf16x8 pa2, bf16x8 pa3) {
;   const s16x4 l0 = tr_read<v_rd_off(D0, 0, 0)>(vb), h0 = tr_read<v_rd_off(D0, 0, 1)>(vb), l1 = tr_read<v_rd_off(D0, 1, 0)>(vb), h1 = tr_read<v_rd_off(D0, 1, 1)>(vb);
;   const s16x4 l2 = tr_read<v_rd_off(D0, 2, 0)>(vb), h2 = tr_read<v_rd_off(D0, 2, 1)>(vb), l3 = tr_read<v_rd_off(D0, 3, 0)>(vb), h3 = tr_read<v_rd_off(D0, 3, 1)>(vb);
;   asm volatile("s_waitcnt lgkmcnt(0)" ::: "memory"); SBAR();
;     ...
;   od = __builtin_amdgcn_mfma_f32_32x32x16_bf16(PK(l0, h0), pa0, od, 0, 0, 0);
;   od = __builtin_amdgcn_mfma_f32_32x32x16_bf16(PK(l1, h1), pa1, od, 0, 0, 0);
;   od = __builtin_amdgcn_mfma_f32_32x32x16_bf16(PK(l2, h2), pa2, od, 0, 0, 0);
;   od = __builtin_amdgcn_mfma_f32_32x32x16_bf16(PK(l3, h3), pa3, od, 0, 0, 0);
;     ...
; }
	v_mfma_f32_32x32x16_bf16 v[0:15], v[200:203], v[144:147], v[0:15]
	ds_read_b64_tr_b16 v[200:201], v196 offset:0x200
	ds_read_b64_tr_b16 v[202:203], v196 offset:0xa00
	s_waitcnt lgkmcnt(6)
	v_mfma_f32_32x32x16_bf16 v[0:15], v[204:207], v[148:151], v[0:15]
	ds_read_b64_tr_b16 v[204:205], v196 offset:0x1200
	ds_read_b64_tr_b16 v[206:207], v196 offset:0x1a00
	s_waitcnt lgkmcnt(6)
	v_mfma_f32_32x32x16_bf16 v[0:15], v[208:211], v[152:155], v[0:15]
	ds_read_b64_tr_b16 v[208:209], v196 offset:0x2200
	ds_read_b64_tr_b16 v[210:211], v196 offset:0x2a00
	s_waitcnt lgkmcnt(6)
	v_mfma_f32_32x32x16_bf16 v[0:15], v[212:215], v[170:173], v[0:15]
	ds_read_b64_tr_b16 v[212:213], v196 offset:0x3200
	ds_read_b64_tr_b16 v[214:215], v196 offset:0x3a00
	s_waitcnt lgkmcnt(6)
	v_mfma_f32_32x32x16_bf16 v[48:63], v[200:203], v[144:147], v[48:63]
	ds_read_b64_tr_b16 v[200:201], v196 offset:0x400
	ds_read_b64_tr_b16 v[202:203], v196 offset:0xc00
	s_waitcnt lgkmcnt(6)
	v_mfma_f32_32x32x16_bf16 v[48:63], v[204:207], v[148:151], v[48:63]
	ds_read_b64_tr_b16 v[204:205], v196 offset:0x1400
	ds_read_b64_tr_b16 v[206:207], v196 offset:0x1c00
	s_waitcnt lgkmcnt(6)
	v_mfma_f32_32x32x16_bf16 v[48:63], v[208:211], v[152:155], v[48:63]
	ds_read_b64_tr_b16 v[208:209], v196 offset:0x2400
	ds_read_b64_tr_b16 v[210:211], v196 offset:0x2c00
	s_waitcnt lgkmcnt(6)
	v_mfma_f32_32x32x16_bf16 v[48:63], v[212:215], v[170:173], v[48:63]
	ds_read_b64_tr_b16 v[212:213], v196 offset:0x3400
	ds_read_b64_tr_b16 v[214:215], v196 offset:0x3c00
	s_waitcnt lgkmcnt(6)
	v_mfma_f32_32x32x16_bf16 v[32:47], v[200:203], v[144:147], v[32:47]
	ds_read_b64_tr_b16 v[200:201], v196 offset:0x600
	ds_read_b64_tr_b16 v[202:203], v196 offset:0xe00
	s_waitcnt lgkmcnt(6)
	v_mfma_f32_32x32x16_bf16 v[32:47], v[204:207], v[148:151], v[32:47]
	ds_read_b64_tr_b16 v[204:205], v196 offset:0x1600
	ds_read_b64_tr_b16 v[206:207], v196 offset:0x1e00
	s_waitcnt lgkmcnt(6)
	v_mfma_f32_32x32x16_bf16 v[32:47], v[208:211], v[152:155], v[32:47]
	ds_read_b64_tr_b16 v[208:209], v196 offset:0x2600
	ds_read_b64_tr_b16 v[210:211], v196 offset:0x2e00
	s_waitcnt lgkmcnt(6)
	v_mfma_f32_32x32x16_bf16 v[32:47], v[212:215], v[170:173], v[32:47]
	ds_read_b64_tr_b16 v[212:213], v196 offset:0x3600
	ds_read_b64_tr_b16 v[214:215], v196 offset:0x3e00
	s_waitcnt lgkmcnt(6)
	v_mfma_f32_32x32x16_bf16 v[16:31], v[200:203], v[144:147], v[16:31]
	v_max_f32_e32 v144, v80, v81
	v_max3_f32 v144, v144, v82, v83
	v_max3_f32 v144, v144, v84, v85
	v_max3_f32 v144, v144, v86, v87
	v_max3_f32 v144, v144, v88, v89
	v_max3_f32 v144, v144, v90, v91
	v_max3_f32 v144, v144, v92, v93
	s_waitcnt lgkmcnt(4)
	v_mfma_f32_32x32x16_bf16 v[16:31], v[204:207], v[148:151], v[16:31]
	v_max3_f32 v144, v144, v94, v95
	v_max3_f32 v144, v144, v64, v65
	v_max3_f32 v144, v144, v66, v67
	v_max3_f32 v144, v144, v68, v69
	v_max3_f32 v144, v144, v70, v71
	v_max3_f32 v144, v144, v72, v73
	v_max3_f32 v144, v144, v74, v75
	v_max3_f32 v144, v144, v76, v77
	s_waitcnt lgkmcnt(2)
	v_mfma_f32_32x32x16_bf16 v[16:31], v[208:211], v[152:155], v[16:31]
	v_max3_f32 v144, v144, v78, v79
	v_mov_b32_e32 v145, v144
	s_nop 1
	v_permlane32_swap_b32_e32 v144, v145
	v_max_f32_e32 v144, v144, v145
	v_cmp_nge_f32_e32 vcc, s63, v144
	s_waitcnt lgkmcnt(0)
	v_mfma_f32_32x32x16_bf16 v[16:31], v[212:215], v[170:173], v[16:31]
	s_waitcnt vmcnt(0) lgkmcnt(0)
	s_barrier
	s_cbranch_vccz .Lal_c_m1
	v_max_f32_e32 v242, 0, v144
	v_exp_f32_e64 v152, -v242
	s_nop 0
	v_pk_mul_f32 v[14:15], v[14:15], v[152:153] op_sel_hi:[1,0]
	v_pk_mul_f32 v[12:13], v[12:13], v[152:153] op_sel_hi:[1,0]
	v_pk_mul_f32 v[10:11], v[10:11], v[152:153] op_sel_hi:[1,0]
	v_pk_mul_f32 v[8:9], v[8:9], v[152:153] op_sel_hi:[1,0]
	v_pk_mul_f32 v[6:7], v[6:7], v[152:153] op_sel_hi:[1,0]
	v_pk_mul_f32 v[4:5], v[4:5], v[152:153] op_sel_hi:[1,0]
	v_pk_mul_f32 v[2:3], v[2:3], v[152:153] op_sel_hi:[1,0]
	v_pk_mul_f32 v[0:1], v[0:1], v[152:153] op_sel_hi:[1,0]
	v_pk_mul_f32 v[62:63], v[62:63], v[152:153] op_sel_hi:[1,0]
	v_pk_mul_f32 v[60:61], v[60:61], v[152:153] op_sel_hi:[1,0]
	v_pk_mul_f32 v[58:59], v[58:59], v[152:153] op_sel_hi:[1,0]
	v_pk_mul_f32 v[56:57], v[56:57], v[152:153] op_sel_hi:[1,0]
	v_pk_mul_f32 v[54:55], v[54:55], v[152:153] op_sel_hi:[1,0]
	v_pk_mul_f32 v[52:53], v[52:53], v[152:153] op_sel_hi:[1,0]
	v_pk_mul_f32 v[50:51], v[50:51], v[152:153] op_sel_hi:[1,0]
	v_pk_mul_f32 v[48:49], v[48:49], v[152:153] op_sel_hi:[1,0]
	v_pk_mul_f32 v[46:47], v[46:47], v[152:153] op_sel_hi:[1,0]
	v_pk_mul_f32 v[44:45], v[44:45], v[152:153] op_sel_hi:[1,0]
	v_pk_mul_f32 v[42:43], v[42:43], v[152:153] op_sel_hi:[1,0]
	v_pk_mul_f32 v[40:41], v[40:41], v[152:153] op_sel_hi:[1,0]
	v_pk_mul_f32 v[38:39], v[38:39], v[152:153] op_sel_hi:[1,0]
	v_pk_mul_f32 v[36:37], v[36:37], v[152:153] op_sel_hi:[1,0]
	v_pk_mul_f32 v[34:35], v[34:35], v[152:153] op_sel_hi:[1,0]
	v_pk_mul_f32 v[32:33], v[32:33], v[152:153] op_sel_hi:[1,0]
	v_pk_mul_f32 v[30:31], v[30:31], v[152:153] op_sel_hi:[1,0]
	v_pk_mul_f32 v[28:29], v[28:29], v[152:153] op_sel_hi:[1,0]
	v_pk_mul_f32 v[26:27], v[26:27], v[152:153] op_sel_hi:[1,0]
	v_pk_mul_f32 v[24:25], v[24:25], v[152:153] op_sel_hi:[1,0]
	v_pk_mul_f32 v[22:23], v[22:23], v[152:153] op_sel_hi:[1,0]
	v_pk_mul_f32 v[20:21], v[20:21], v[152:153] op_sel_hi:[1,0]
	v_pk_mul_f32 v[18:19], v[18:19], v[152:153] op_sel_hi:[1,0]
	v_pk_mul_f32 v[16:17], v[16:17], v[152:153] op_sel_hi:[1,0]
	v_sub_f32_e32 v80, v80, v242
	v_sub_f32_e32 v81, v81, v242
	v_sub_f32_e32 v82, v82, v242
	v_sub_f32_e32 v83, v83, v242
	v_sub_f32_e32 v84, v84, v242
	v_sub_f32_e32 v85, v85, v242
	v_sub_f32_e32 v86, v86, v242
	v_sub_f32_e32 v87, v87, v242
	v_sub_f32_e32 v88, v88, v242
	v_sub_f32_e32 v89, v89, v242
	v_sub_f32_e32 v90, v90, v242
	v_sub_f32_e32 v91, v91, v242
	v_sub_f32_e32 v92, v92, v242
	v_sub_f32_e32 v93, v93, v242
	v_sub_f32_e32 v94, v94, v242
	v_sub_f32_e32 v95, v95, v242
	v_sub_f32_e32 v64, v64, v242
	v_sub_f32_e32 v65, v65, v242
	v_sub_f32_e32 v66, v66, v242
	v_sub_f32_e32 v67, v67, v242
	v_sub_f32_e32 v68, v68, v242
	v_sub_f32_e32 v69, v69, v242
	v_sub_f32_e32 v70, v70, v242
	v_sub_f32_e32 v71, v71, v242
	v_sub_f32_e32 v72, v72, v242
	v_sub_f32_e32 v73, v73, v242
	v_sub_f32_e32 v74, v74, v242
	v_sub_f32_e32 v75, v75, v242
	v_sub_f32_e32 v76, v76, v242
	v_sub_f32_e32 v77, v77, v242
	v_sub_f32_e32 v78, v78, v242
	v_sub_f32_e32 v79, v79, v242
	v_sub_f32_e32 v226, v226, v242
	v_sub_f32_e32 v227, v227, v242
	v_sub_f32_e32 v228, v228, v242
	v_sub_f32_e32 v229, v229, v242
	v_sub_f32_e32 v230, v230, v242
	v_sub_f32_e32 v231, v231, v242
	v_sub_f32_e32 v232, v232, v242
	v_sub_f32_e32 v233, v233, v242
	v_sub_f32_e32 v234, v234, v242
	v_sub_f32_e32 v235, v235, v242
	v_sub_f32_e32 v236, v236, v242
	v_sub_f32_e32 v237, v237, v242
	v_sub_f32_e32 v238, v238, v242
	v_sub_f32_e32 v239, v239, v242
	v_sub_f32_e32 v240, v240, v242
	v_sub_f32_e32 v241, v241, v242
	s_branch .LBB0_117

; __device__ __forceinline__ void finishSM(f32x16& p0, f32x16& p1, float alpha, float& l_reg, bf16x8& pa0, bf16x8& pa1, bf16x8& pa2, bf16x8& pa3) {
; #pragma unroll
;   for (int r = 0; r < 16; ++r) p1[r] = __builtin_amdgcn_exp2f(p1[r]);
;   float ps = 0;
; #pragma unroll
;   for (int r = 0; r < 16; ++r) ps += p0[r];
; #pragma unroll
;   for (int r = 0; r < 16; ++r) ps += p1[r];
;   { auto rr = __builtin_amdgcn_permlane32_swap(__float_as_uint(ps), __float_as_uint(ps), false, false);
;     ps = __uint_as_float(rr[0]) + __uint_as_float(rr[1]); }
;   l_reg = l_reg * alpha + ps;
;     ...
;   PK4(p0, 0, pa0); PK4(p0, 8, pa1); PK4(p1, 0, pa2); PK4(p1, 8, pa3);
; template <int BUFOFF>
; __device__ __forceinline__ void qkt_mla(f32x16& p0, f32x16& p1, const int* ka, const bf16x8* qr, const char* qlds) {
;   typedef __attribute__((address_space(3))) const bf16x8* lp;
;   p0 = f32x16{}; p1 = f32x16{};
; #pragma unroll
;   for (int d0 = 0; d0 < 12; ++d0) {
;     const int a = ka[d0 & 3] + (d0 >> 2) * 128 + BUFOFF;
;     const bf16x8 b0 = *(lp)(a), b1 = *(lp)(a + 12288);
;     bf16x8 qf;
;     qf = qr[d0];
;     p0 = __builtin_amdgcn_mfma_f32_32x32x16_bf16(b0, qf, p0, 0, 0, 0);
;     p1 = __builtin_amdgcn_mfma_f32_32x32x16_bf16(b1, qf, p1, 0, 0, 0);
;   }
; }
.LBB0_117:
	v_exp_f32_e32 v155, v64
	v_exp_f32_e32 v170, v65
	v_exp_f32_e32 v171, v66
	v_exp_f32_e32 v172, v67
	v_exp_f32_e32 v173, v68
	v_exp_f32_e32 v197, v69
	v_exp_f32_e32 v199, v70
	v_exp_f32_e32 v200, v71
	v_exp_f32_e32 v201, v72
	v_exp_f32_e32 v202, v73
	v_exp_f32_e32 v203, v74
	v_exp_f32_e32 v204, v75
	v_exp_f32_e32 v205, v76
	v_exp_f32_e32 v222, v77
	v_exp_f32_e32 v223, v78
	v_exp_f32_e32 v154, v79
	v_exp_f32_e32 v206, v80
	v_exp_f32_e32 v207, v81
	v_exp_f32_e32 v208, v82
	v_exp_f32_e32 v209, v83
	v_exp_f32_e32 v210, v84
	v_exp_f32_e32 v211, v85
	v_exp_f32_e32 v212, v86
	v_exp_f32_e32 v213, v87
	v_exp_f32_e32 v214, v88
	v_exp_f32_e32 v215, v89
	v_exp_f32_e32 v216, v90
	v_exp_f32_e32 v217, v91
	v_exp_f32_e32 v218, v92
	v_exp_f32_e32 v219, v93
	v_exp_f32_e32 v220, v94
	v_exp_f32_e32 v221, v95
	ds_read_b128 v[64:67], v169
	ds_read_b128 v[68:71], v169 offset:12288
	ds_read_b128 v[144:147], v190
	ds_read_b128 v[148:151], v190 offset:12288
	v_mov_b32_e32 v224, v155
	s_waitcnt lgkmcnt(0)
	v_mfma_f32_32x32x16_bf16 v[80:95], v[64:67], v[140:143], v[226:241]
	v_mfma_f32_32x32x16_bf16 v[64:79], v[68:71], v[140:143], v[226:241]
	v_mov_b32_e32 v225, v154
	v_mfma_f32_32x32x16_bf16 v[80:95], v[144:147], v[136:139], v[80:95]
	v_mfma_f32_32x32x16_bf16 v[64:79], v[148:151], v[136:139], v[64:79]
	ds_read_b128 v[144:147], v193
	ds_read_b128 v[148:151], v193 offset:12288
	s_waitcnt lgkmcnt(0)
	v_mfma_f32_32x32x16_bf16 v[80:95], v[144:147], v[132:135], v[80:95]
	v_mfma_f32_32x32x16_bf16 v[64:79], v[148:151], v[132:135], v[64:79]
	ds_read_b128 v[144:147], v192
	ds_read_b128 v[148:151], v192 offset:12288
	s_waitcnt lgkmcnt(0)
	v_mfma_f32_32x32x16_bf16 v[80:95], v[144:147], v[128:131], v[80:95]
	v_mfma_f32_32x32x16_bf16 v[64:79], v[148:151], v[128:131], v[64:79]
	ds_read_b128 v[144:147], v169 offset:128
	ds_read_b128 v[148:151], v169 offset:12416
	s_waitcnt lgkmcnt(0)
	v_mfma_f32_32x32x16_bf16 v[80:95], v[144:147], v[124:127], v[80:95]
	v_mfma_f32_32x32x16_bf16 v[64:79], v[148:151], v[124:127], v[64:79]
	ds_read_b128 v[144:147], v190 offset:128
	ds_read_b128 v[148:151], v190 offset:12416
	s_waitcnt lgkmcnt(0)
	v_mfma_f32_32x32x16_bf16 v[80:95], v[144:147], v[120:123], v[80:95]
	v_mfma_f32_32x32x16_bf16 v[64:79], v[148:151], v[120:123], v[64:79]
	ds_read_b128 v[144:147], v193 offset:128
	ds_read_b128 v[148:151], v193 offset:12416
	s_waitcnt lgkmcnt(0)
	v_mfma_f32_32x32x16_bf16 v[80:95], v[144:147], v[116:119], v[80:95]
	v_mfma_f32_32x32x16_bf16 v[64:79], v[148:151], v[116:119], v[64:79]
	ds_read_b128 v[144:147], v192 offset:128
	ds_read_b128 v[148:151], v192 offset:12416
	s_waitcnt lgkmcnt(0)
	v_mfma_f32_32x32x16_bf16 v[80:95], v[144:147], v[112:115], v[80:95]
	v_mfma_f32_32x32x16_bf16 v[64:79], v[148:151], v[112:115], v[64:79]
	ds_read_b128 v[144:147], v169 offset:256
	ds_read_b128 v[148:151], v169 offset:12544
	s_waitcnt lgkmcnt(0)
	v_mfma_f32_32x32x16_bf16 v[80:95], v[144:147], v[108:111], v[80:95]
	v_mfma_f32_32x32x16_bf16 v[64:79], v[148:151], v[108:111], v[64:79]
	ds_read_b128 v[144:147], v190 offset:256
	ds_read_b128 v[148:151], v190 offset:12544
	s_waitcnt lgkmcnt(0)
	v_mfma_f32_32x32x16_bf16 v[80:95], v[144:147], v[104:107], v[80:95]
	v_mfma_f32_32x32x16_bf16 v[64:79], v[148:151], v[104:107], v[64:79]
	ds_read_b128 v[144:147], v193 offset:256
	ds_read_b128 v[148:151], v193 offset:12544
	s_waitcnt lgkmcnt(0)
	v_mfma_f32_32x32x16_bf16 v[80:95], v[144:147], v[100:103], v[80:95]
	v_mfma_f32_32x32x16_bf16 v[64:79], v[148:151], v[100:103], v[64:79]
	ds_read_b128 v[144:147], v192 offset:256
	ds_read_b128 v[148:151], v192 offset:12544
	s_waitcnt lgkmcnt(0)
	v_mfma_f32_32x32x16_bf16 v[80:95], v[144:147], v[96:99], v[80:95]
	v_add_f32_e32 v144, v214, v206
	v_add_f32_e32 v243, v215, v207
	v_add_f32_e32 v244, v216, v208
	v_add_f32_e32 v245, v217, v209
	v_add_f32_e32 v246, v218, v210
	v_add_f32_e32 v247, v219, v211
	v_add_f32_e32 v251, v220, v212
	v_add_f32_e32 v252, v221, v213
	v_add_f32_e32 v144, v224, v144
	v_add_f32_e32 v243, v170, v243
	v_add_f32_e32 v244, v171, v244
	v_add_f32_e32 v245, v172, v245
	v_add_f32_e32 v246, v173, v246
	v_add_f32_e32 v247, v197, v247
	v_add_f32_e32 v251, v199, v251
	v_add_f32_e32 v252, v200, v252
	v_add_f32_e32 v144, v201, v144
	v_add_f32_e32 v243, v202, v243
	v_mfma_f32_32x32x16_bf16 v[64:79], v[148:151], v[96:99], v[64:79]
	v_add_f32_e32 v244, v203, v244
	v_add_f32_e32 v245, v204, v245
	v_add_f32_e32 v246, v205, v246
	v_add_f32_e32 v247, v222, v247
	v_add_f32_e32 v251, v223, v251
	v_add_f32_e32 v252, v225, v252
	v_add_f32_e32 v144, v144, v243
	v_add_f32_e32 v244, v244, v245
	v_add_f32_e32 v246, v246, v247
	v_add_f32_e32 v251, v251, v252
	v_add_f32_e32 v144, v144, v244
	v_add_f32_e32 v246, v246, v251
	v_add_f32_e32 v154, v144, v246
	v_mov_b32_e32 v155, v154
	v_cvt_pk_bf16_f32 v144, v206, v207
	v_cvt_pk_bf16_f32 v145, v208, v209
	v_cvt_pk_bf16_f32 v146, v210, v211
	v_cvt_pk_bf16_f32 v147, v212, v213
	s_nop 1
	v_permlane32_swap_b32_e32 v154, v155
	v_cvt_pk_bf16_f32 v148, v214, v215
	v_cvt_pk_bf16_f32 v149, v216, v217
	v_cvt_pk_bf16_f32 v150, v218, v219
	v_cvt_pk_bf16_f32 v151, v220, v221
	v_cvt_pk_bf16_f32 v170, v224, v170
	v_cvt_pk_bf16_f32 v171, v171, v172
	v_cvt_pk_bf16_f32 v172, v173, v197
	v_cvt_pk_bf16_f32 v173, v199, v200
	v_cvt_pk_bf16_f32 v200, v201, v202
	v_cvt_pk_bf16_f32 v201, v203, v204
	v_cvt_pk_bf16_f32 v202, v205, v222
	v_cvt_pk_bf16_f32 v203, v223, v225
	s_nop 0
	s_add_u32 s4, s56, 0x17090000
	s_addc_u32 s5, s57, 0
	s_add_u32 s56, s58, 0x1a060000
	s_mov_b32 m0, s16
	s_addc_u32 s57, s59, 0
	s_add_i32 s58, s40, s60
	global_load_lds_dwordx4 v188, s[4:5]
	s_mov_b32 m0, s17
	s_nop 0
	global_load_lds_dwordx4 v189, s[4:5]
	s_mov_b32 m0, s44
	s_nop 0
	global_load_lds_dwordx4 v191, s[4:5]
	s_mov_b32 m0, s58
	s_nop 0
	global_load_lds_dwordx4 v194, s[56:57]
	s_add_i32 m0, s58, 0x2000
	s_nop 0
	global_load_lds_dwordx4 v195, s[56:57]
	v_lshl_add_u32 v197, s55, 14, v167
	ds_read_b64_tr_b16 v[204:205], v197 offset:0
	ds_read_b64_tr_b16 v[206:207], v197 offset:0x800
	ds_read_b64_tr_b16 v[208:209], v197 offset:0x1000
	ds_read_b64_tr_b16 v[210:211], v197 offset:0x1800
	ds_read_b64_tr_b16 v[212:213], v197 offset:0x2000
	ds_read_b64_tr_b16 v[214:215], v197 offset:0x2800
	ds_read_b64_tr_b16 v[216:217], v197 offset:0x3000
	ds_read_b64_tr_b16 v[218:219], v197 offset:0x3800
	s_nop 0
	s_waitcnt lgkmcnt(6)
; #define SBAR() __builtin_amdgcn_sched_barrier(0)
; template <int MLA>
; __device__ __forceinline__ void partialSM(f32x16& p0, f32x16& p1, float& m_reg, float& mn, float& alpha) {
;     ...
;   float pmax = p0[0];
; #pragma unroll
;   for (int r = 1; r < 16; ++r) pmax = fmaxf(pmax, p0[r]);
; #pragma unroll
;   for (int r = 0; r < 16; ++r) pmax = fmaxf(pmax, p1[r]);
;   { auto rr = __builtin_amdgcn_permlane32_swap(__float_as_uint(pmax), __float_as_uint(pmax), false, false);
;     pmax = fmaxf(__uint_as_float(rr[0]), __uint_as_float(rr[1])); }
;   if (__builtin_expect(__all(pmax - m_reg <= THR / SCALE), 1)) { mn = m_reg; alpha = 1.f; }
;   else { mn = fmaxf(m_reg, pmax); alpha = __builtin_amdgcn_exp2f((m_reg - mn) * C); m_reg = mn; }
;   float mnC = -mn * C;
; #pragma unroll
;   for (int r = 0; r < 16; ++r) p0[r] = fmaf(p0[r], C, mnC);
; #pragma unroll
;   for (int r = 0; r < 16; ++r) p1[r] = fmaf(p1[r], C, mnC);
; template <int D0> __device__ __forceinline__ void pv_one_t(f32x16& od, int vb, bf16x8 pa0, bf16x8 pa1, bf16x8 pa2, bf16x8 pa3) {
;   const s16x4 l0 = tr_read<v_rd_off(D0, 0, 0)>(vb), h0 = tr_read<v_rd_off(D0, 0, 1)>(vb), l1 = tr_read<v_rd_off(D0, 1, 0)>(vb), h1 = tr_read<v_rd_off(D0, 1, 1)>(vb);
;   const s16x4 l2 = tr_read<v_rd_off(D0, 2, 0)>(vb), h2 = tr_read<v_rd_off(D0, 2, 1)>(vb), l3 = tr_read<v_rd_off(D0, 3, 0)>(vb), h3 = tr_read<v_rd_off(D0, 3, 1)>(vb);
;   asm volatile("s_waitcnt lgkmcnt(0)" ::: "memory"); SBAR();
;     ...
;   od = __builtin_amdgcn_mfma_f32_32x32x16_bf16(PK(l0, h0), pa0, od, 0, 0, 0);
;   od = __builtin_amdgcn_mfma_f32_32x32x16_bf16(PK(l1, h1), pa1, od, 0, 0, 0);
;   od = __builtin_amdgcn_mfma_f32_32x32x16_bf16(PK(l2, h2), pa2, od, 0, 0, 0);
;   od = __builtin_amdgcn_mfma_f32_32x32x16_bf16(PK(l3, h3), pa3, od, 0, 0, 0);
;     ...
; }
	v_mfma_f32_32x32x16_bf16 v[0:15], v[204:207], v[144:147], v[0:15]
	ds_read_b64_tr_b16 v[204:205], v197 offset:0x200
	ds_read_b64_tr_b16 v[206:207], v197 offset:0xa00
	s_waitcnt lgkmcnt(6)
	v_mfma_f32_32x32x16_bf16 v[0:15], v[208:211], v[148:151], v[0:15]
	ds_read_b64_tr_b16 v[208:209], v197 offset:0x1200
	ds_read_b64_tr_b16 v[210:211], v197 offset:0x1a00
	s_waitcnt lgkmcnt(6)
	v_mfma_f32_32x32x16_bf16 v[0:15], v[212:215], v[170:173], v[0:15]
	ds_read_b64_tr_b16 v[212:213], v197 offset:0x2200
	ds_read_b64_tr_b16 v[214:215], v197 offset:0x2a00
	s_waitcnt lgkmcnt(6)
	v_mfma_f32_32x32x16_bf16 v[0:15], v[216:219], v[200:203], v[0:15]
	ds_read_b64_tr_b16 v[216:217], v197 offset:0x3200
	ds_read_b64_tr_b16 v[218:219], v197 offset:0x3a00
	s_waitcnt lgkmcnt(6)
	v_mfma_f32_32x32x16_bf16 v[48:63], v[204:207], v[144:147], v[48:63]
	ds_read_b64_tr_b16 v[204:205], v197 offset:0x400
	ds_read_b64_tr_b16 v[206:207], v197 offset:0xc00
	s_waitcnt lgkmcnt(6)
	v_mfma_f32_32x32x16_bf16 v[48:63], v[208:211], v[148:151], v[48:63]
	ds_read_b64_tr_b16 v[208:209], v197 offset:0x1400
	ds_read_b64_tr_b16 v[210:211], v197 offset:0x1c00
	s_waitcnt lgkmcnt(6)
	v_mfma_f32_32x32x16_bf16 v[48:63], v[212:215], v[170:173], v[48:63]
	ds_read_b64_tr_b16 v[212:213], v197 offset:0x2400
	ds_read_b64_tr_b16 v[214:215], v197 offset:0x2c00
	s_waitcnt lgkmcnt(6)
	v_mfma_f32_32x32x16_bf16 v[48:63], v[216:219], v[200:203], v[48:63]
	ds_read_b64_tr_b16 v[216:217], v197 offset:0x3400
	ds_read_b64_tr_b16 v[218:219], v197 offset:0x3c00
	s_waitcnt lgkmcnt(6)
	v_mfma_f32_32x32x16_bf16 v[32:47], v[204:207], v[144:147], v[32:47]
	ds_read_b64_tr_b16 v[204:205], v197 offset:0x600
	ds_read_b64_tr_b16 v[206:207], v197 offset:0xe00
	s_waitcnt lgkmcnt(6)
	v_mfma_f32_32x32x16_bf16 v[32:47], v[208:211], v[148:151], v[32:47]
	ds_read_b64_tr_b16 v[208:209], v197 offset:0x1600
	ds_read_b64_tr_b16 v[210:211], v197 offset:0x1e00
	s_waitcnt lgkmcnt(6)
	v_mfma_f32_32x32x16_bf16 v[32:47], v[212:215], v[170:173], v[32:47]
	ds_read_b64_tr_b16 v[212:213], v197 offset:0x2600
	ds_read_b64_tr_b16 v[214:215], v197 offset:0x2e00
	s_waitcnt lgkmcnt(6)
	v_mfma_f32_32x32x16_bf16 v[32:47], v[216:219], v[200:203], v[32:47]
	ds_read_b64_tr_b16 v[216:217], v197 offset:0x3600
	ds_read_b64_tr_b16 v[218:219], v197 offset:0x3e00
	s_waitcnt lgkmcnt(6)
	v_mfma_f32_32x32x16_bf16 v[16:31], v[204:207], v[144:147], v[16:31]
	v_max_f32_e32 v144, v80, v81
	v_max3_f32 v144, v144, v82, v83
	v_max3_f32 v144, v144, v84, v85
	v_max3_f32 v144, v144, v86, v87
	v_max3_f32 v144, v144, v88, v89
	v_max3_f32 v144, v144, v90, v91
	v_max3_f32 v144, v144, v92, v93
	s_waitcnt lgkmcnt(4)
	v_mfma_f32_32x32x16_bf16 v[16:31], v[208:211], v[148:151], v[16:31]
	v_max3_f32 v144, v144, v94, v95
	v_max3_f32 v144, v144, v64, v65
	v_max3_f32 v144, v144, v66, v67
	v_max3_f32 v144, v144, v68, v69
	v_max3_f32 v144, v144, v70, v71
	v_max3_f32 v144, v144, v72, v73
	v_max3_f32 v144, v144, v74, v75
	v_max3_f32 v144, v144, v76, v77
	s_waitcnt lgkmcnt(2)
	v_mfma_f32_32x32x16_bf16 v[16:31], v[212:215], v[170:173], v[16:31]
	v_max3_f32 v144, v144, v78, v79
	v_mov_b32_e32 v145, v144
	s_nop 1
	v_permlane32_swap_b32_e32 v144, v145
	v_max_f32_e32 v144, v144, v145
	v_cmp_nge_f32_e32 vcc, s63, v144
	s_waitcnt lgkmcnt(0)
	v_mfma_f32_32x32x16_bf16 v[16:31], v[216:219], v[200:203], v[16:31]
	s_waitcnt vmcnt(0) lgkmcnt(0)
	s_barrier
	s_cbranch_vccz .Lal_c_m2
	v_max_f32_e32 v242, 0, v144
	v_exp_f32_e64 v144, -v242
	s_nop 0
	v_pk_mul_f32 v[14:15], v[14:15], v[144:145] op_sel_hi:[1,0]
	v_pk_mul_f32 v[12:13], v[12:13], v[144:145] op_sel_hi:[1,0]
	v_pk_mul_f32 v[10:11], v[10:11], v[144:145] op_sel_hi:[1,0]
	v_pk_mul_f32 v[8:9], v[8:9], v[144:145] op_sel_hi:[1,0]
	v_pk_mul_f32 v[6:7], v[6:7], v[144:145] op_sel_hi:[1,0]
	v_pk_mul_f32 v[4:5], v[4:5], v[144:145] op_sel_hi:[1,0]
	v_pk_mul_f32 v[2:3], v[2:3], v[144:145] op_sel_hi:[1,0]
	v_pk_mul_f32 v[0:1], v[0:1], v[144:145] op_sel_hi:[1,0]
	v_pk_mul_f32 v[62:63], v[62:63], v[144:145] op_sel_hi:[1,0]
	v_pk_mul_f32 v[60:61], v[60:61], v[144:145] op_sel_hi:[1,0]
	v_pk_mul_f32 v[58:59], v[58:59], v[144:145] op_sel_hi:[1,0]
	v_pk_mul_f32 v[56:57], v[56:57], v[144:145] op_sel_hi:[1,0]
	v_pk_mul_f32 v[54:55], v[54:55], v[144:145] op_sel_hi:[1,0]
	v_pk_mul_f32 v[52:53], v[52:53], v[144:145] op_sel_hi:[1,0]
	v_pk_mul_f32 v[50:51], v[50:51], v[144:145] op_sel_hi:[1,0]
	v_pk_mul_f32 v[48:49], v[48:49], v[144:145] op_sel_hi:[1,0]
	v_pk_mul_f32 v[46:47], v[46:47], v[144:145] op_sel_hi:[1,0]
	v_pk_mul_f32 v[44:45], v[44:45], v[144:145] op_sel_hi:[1,0]
	v_pk_mul_f32 v[42:43], v[42:43], v[144:145] op_sel_hi:[1,0]
	v_pk_mul_f32 v[40:41], v[40:41], v[144:145] op_sel_hi:[1,0]
	v_pk_mul_f32 v[38:39], v[38:39], v[144:145] op_sel_hi:[1,0]
	v_pk_mul_f32 v[36:37], v[36:37], v[144:145] op_sel_hi:[1,0]
	v_pk_mul_f32 v[34:35], v[34:35], v[144:145] op_sel_hi:[1,0]
	v_pk_mul_f32 v[32:33], v[32:33], v[144:145] op_sel_hi:[1,0]
	v_pk_mul_f32 v[30:31], v[30:31], v[144:145] op_sel_hi:[1,0]
	v_pk_mul_f32 v[28:29], v[28:29], v[144:145] op_sel_hi:[1,0]
	v_pk_mul_f32 v[26:27], v[26:27], v[144:145] op_sel_hi:[1,0]
	v_pk_mul_f32 v[24:25], v[24:25], v[144:145] op_sel_hi:[1,0]
	v_pk_mul_f32 v[22:23], v[22:23], v[144:145] op_sel_hi:[1,0]
	v_pk_mul_f32 v[20:21], v[20:21], v[144:145] op_sel_hi:[1,0]
	v_pk_mul_f32 v[18:19], v[18:19], v[144:145] op_sel_hi:[1,0]
	v_pk_mul_f32 v[16:17], v[16:17], v[144:145] op_sel_hi:[1,0]
	v_sub_f32_e32 v80, v80, v242
	v_sub_f32_e32 v81, v81, v242
	v_sub_f32_e32 v82, v82, v242
	v_sub_f32_e32 v83, v83, v242
	v_sub_f32_e32 v84, v84, v242
	v_sub_f32_e32 v85, v85, v242
	v_sub_f32_e32 v86, v86, v242
	v_sub_f32_e32 v87, v87, v242
	v_sub_f32_e32 v88, v88, v242
	v_sub_f32_e32 v89, v89, v242
	v_sub_f32_e32 v90, v90, v242
	v_sub_f32_e32 v91, v91, v242
	v_sub_f32_e32 v92, v92, v242
	v_sub_f32_e32 v93, v93, v242
	v_sub_f32_e32 v94, v94, v242
	v_sub_f32_e32 v95, v95, v242
	v_sub_f32_e32 v64, v64, v242
	v_sub_f32_e32 v65, v65, v242
	v_sub_f32_e32 v66, v66, v242
	v_sub_f32_e32 v67, v67, v242
	v_sub_f32_e32 v68, v68, v242
	v_sub_f32_e32 v69, v69, v242
	v_sub_f32_e32 v70, v70, v242
	v_sub_f32_e32 v71, v71, v242
	v_sub_f32_e32 v72, v72, v242
	v_sub_f32_e32 v73, v73, v242
	v_sub_f32_e32 v74, v74, v242
	v_sub_f32_e32 v75, v75, v242
	v_sub_f32_e32 v76, v76, v242
	v_sub_f32_e32 v77, v77, v242
	v_sub_f32_e32 v78, v78, v242
	v_sub_f32_e32 v79, v79, v242
	v_sub_f32_e32 v226, v226, v242
	v_sub_f32_e32 v227, v227, v242
	v_sub_f32_e32 v228, v228, v242
	v_sub_f32_e32 v229, v229, v242
	v_sub_f32_e32 v230, v230, v242
	v_sub_f32_e32 v231, v231, v242
	v_sub_f32_e32 v232, v232, v242
	v_sub_f32_e32 v233, v233, v242
	v_sub_f32_e32 v234, v234, v242
	v_sub_f32_e32 v235, v235, v242
	v_sub_f32_e32 v236, v236, v242
	v_sub_f32_e32 v237, v237, v242
	v_sub_f32_e32 v238, v238, v242
	v_sub_f32_e32 v239, v239, v242
	v_sub_f32_e32 v240, v240, v242
	v_sub_f32_e32 v241, v241, v242
	s_branch .LBB0_119

; __device__ __forceinline__ void finishSM(f32x16& p0, f32x16& p1, float alpha, float& l_reg, bf16x8& pa0, bf16x8& pa1, bf16x8& pa2, bf16x8& pa3) {
; #pragma unroll
;   for (int r = 0; r < 16; ++r) p1[r] = __builtin_amdgcn_exp2f(p1[r]);
;   float ps = 0;
; #pragma unroll
;   for (int r = 0; r < 16; ++r) ps += p0[r];
; #pragma unroll
;   for (int r = 0; r < 16; ++r) ps += p1[r];
;   { auto rr = __builtin_amdgcn_permlane32_swap(__float_as_uint(ps), __float_as_uint(ps), false, false);
;     ps = __uint_as_float(rr[0]) + __uint_as_float(rr[1]); }
;   l_reg = l_reg * alpha + ps;
;     ...
;   PK4(p0, 0, pa0); PK4(p0, 8, pa1); PK4(p1, 0, pa2); PK4(p1, 8, pa3);
; template <int BUFOFF>
; __device__ __forceinline__ void qkt_diff(f32x16& p0, f32x16& p1, const int* ka, const bf16x8* qr) {
;   typedef __attribute__((address_space(3))) const bf16x8* lp;
;   p0 = f32x16{}; p1 = f32x16{};
; #pragma unroll
;   for (int d0 = 0; d0 < 4; ++d0) {
;     const int a = ka[d0] + BUFOFF;
;     const bf16x8 b0 = *(lp)(a), b1 = *(lp)(a + 8192);
;     p0 = __builtin_amdgcn_mfma_f32_32x32x16_bf16(b0, qr[d0], p0, 0, 0, 0);
;     p1 = __builtin_amdgcn_mfma_f32_32x32x16_bf16(b1, qr[d0], p1, 0, 0, 0);
;   }
; }
.LBB0_129:
	s_mov_b32 s54, s47
	s_mov_b32 s47, s52
	ds_read_b128 v[64:67], v138 offset:16384
	ds_read_b128 v[68:71], v138 offset:24576
	ds_read_b128 v[170:173], v141 offset:16384
	ds_read_b128 v[188:191], v141 offset:24576
	s_waitcnt lgkmcnt(0)
	v_mfma_f32_32x32x16_bf16 v[80:95], v[64:67], v[108:111], v[226:241]
	v_add_f32_e32 v112, v144, v113
	v_mfma_f32_32x32x16_bf16 v[64:79], v[68:71], v[108:111], v[226:241]
	v_add_f32_e32 v243, v148, v155
	v_add_f32_e32 v244, v145, v152
	v_add_f32_e32 v245, v149, v156
	v_add_f32_e32 v246, v146, v153
	v_add_f32_e32 v247, v150, v158
	v_mfma_f32_32x32x16_bf16 v[80:95], v[170:173], v[104:107], v[80:95]
	v_add_f32_e32 v251, v147, v154
	v_add_f32_e32 v252, v151, v159
	v_mov_b32_e32 v132, v124
	v_add_f32_e32 v112, v128, v112
	v_mov_b32_e32 v162, v125
	v_mfma_f32_32x32x16_bf16 v[64:79], v[188:191], v[104:107], v[64:79]
	ds_read_b128 v[170:173], v140 offset:16384
	ds_read_b128 v[188:191], v140 offset:24576
	v_add_f32_e32 v243, v129, v243
	v_mov_b32_e32 v167, v120
	v_add_f32_e32 v244, v126, v244
	v_mov_b32_e32 v169, v121
	v_add_f32_e32 v245, v127, v245
	v_add_f32_e32 v246, v132, v246
	s_waitcnt lgkmcnt(0)
	v_mfma_f32_32x32x16_bf16 v[80:95], v[170:173], v[100:103], v[80:95]
	v_add_f32_e32 v247, v162, v247
	v_add_f32_e32 v251, v167, v251
	v_add_f32_e32 v252, v169, v252
	v_mfma_f32_32x32x16_bf16 v[64:79], v[188:191], v[100:103], v[64:79]
	ds_read_b128 v[170:173], v139 offset:16384
	ds_read_b128 v[188:191], v139 offset:24576
	s_waitcnt lgkmcnt(0)
	v_mfma_f32_32x32x16_bf16 v[80:95], v[170:173], v[96:99], v[80:95]
	v_mov_b32_e32 v170, v118
	v_mov_b32_e32 v171, v117
	v_mov_b32_e32 v172, v114
	v_mov_b32_e32 v173, v115
	v_add_f32_e32 v112, v170, v112
	v_add_f32_e32 v243, v119, v243
	v_add_f32_e32 v244, v116, v244
	v_mfma_f32_32x32x16_bf16 v[64:79], v[188:191], v[96:99], v[64:79]
	v_mov_b32_e32 v188, v122
	v_mov_b32_e32 v189, v123
	v_add_f32_e32 v245, v171, v245
	v_add_f32_e32 v246, v172, v246
	v_add_f32_e32 v247, v173, v247
	v_add_f32_e32 v251, v188, v251
	v_add_f32_e32 v252, v189, v252
	v_add_f32_e32 v112, v112, v243
	v_add_f32_e32 v244, v244, v245
	v_add_f32_e32 v246, v246, v247
	v_add_f32_e32 v251, v251, v252
	v_add_f32_e32 v112, v112, v244
	v_add_f32_e32 v246, v246, v251
	v_add_f32_e32 v117, v112, v246
	v_mov_b32_e32 v118, v117
	v_cvt_pk_bf16_f32 v112, v113, v155
	v_cvt_pk_bf16_f32 v113, v152, v156
	v_cvt_pk_bf16_f32 v114, v153, v158
	s_nop 1
	v_permlane32_swap_b32_e32 v117, v118
	v_cvt_pk_bf16_f32 v115, v154, v159
	v_cvt_pk_bf16_f32 v120, v144, v148
	v_cvt_pk_bf16_f32 v121, v145, v149
	v_cvt_pk_bf16_f32 v122, v146, v150
	v_cvt_pk_bf16_f32 v123, v147, v151
	v_cvt_pk_bf16_f32 v124, v128, v129
	v_cvt_pk_bf16_f32 v125, v126, v127
	v_cvt_pk_bf16_f32 v126, v132, v162
	v_cvt_pk_bf16_f32 v127, v167, v169
	v_cvt_pk_bf16_f32 v144, v170, v119
	v_cvt_pk_bf16_f32 v145, v116, v171
	v_cvt_pk_bf16_f32 v146, v172, v173
	v_cvt_pk_bf16_f32 v147, v188, v189
	s_add_u32 s4, s14, 0x2000000
	s_mov_b32 m0, s43
	s_addc_u32 s5, s15, 0
	s_mov_b64 s[56:57], s[14:15]
	s_lshl_b32 s52, s53, 14
	s_add_i32 s55, s42, s52
	s_nop 0
	global_load_lds_dwordx4 v134, s[56:57]
	s_mov_b32 m0, s44
	s_nop 0
	global_load_lds_dwordx4 v135, s[56:57]
	s_mov_b32 m0, s55
	s_nop 0
	global_load_lds_dwordx4 v136, s[4:5]
	s_add_i32 m0, s55, 0x2000
	s_nop 0
	global_load_lds_dwordx4 v137, s[4:5]
	s_lshl_b32 s55, s47, 14
	v_add_u32_e32 v132, s55, v133
	ds_read_b64_tr_b16 v[148:149], v132 offset:0
	ds_read_b64_tr_b16 v[150:151], v132 offset:0x800
	ds_read_b64_tr_b16 v[152:153], v132 offset:0x1000
	ds_read_b64_tr_b16 v[154:155], v132 offset:0x1800
	ds_read_b64_tr_b16 v[170:171], v132 offset:0x2000
	ds_read_b64_tr_b16 v[172:173], v132 offset:0x2800
	ds_read_b64_tr_b16 v[188:189], v132 offset:0x3000
	ds_read_b64_tr_b16 v[190:191], v132 offset:0x3800
	s_nop 0
	s_waitcnt lgkmcnt(6)
	v_mfma_f32_32x32x16_bf16 v[32:47], v[148:151], v[112:115], v[32:47]
	ds_read_b64_tr_b16 v[148:149], v132 offset:0x200
	ds_read_b64_tr_b16 v[150:151], v132 offset:0xa00
	s_waitcnt lgkmcnt(6)
	v_mfma_f32_32x32x16_bf16 v[32:47], v[152:155], v[120:123], v[32:47]
	ds_read_b64_tr_b16 v[152:153], v132 offset:0x1200
	ds_read_b64_tr_b16 v[154:155], v132 offset:0x1a00
	s_waitcnt lgkmcnt(6)
	v_mfma_f32_32x32x16_bf16 v[32:47], v[170:173], v[124:127], v[32:47]
	ds_read_b64_tr_b16 v[170:171], v132 offset:0x2200
	ds_read_b64_tr_b16 v[172:173], v132 offset:0x2a00
	s_waitcnt lgkmcnt(6)
	v_mfma_f32_32x32x16_bf16 v[32:47], v[188:191], v[144:147], v[32:47]
	ds_read_b64_tr_b16 v[188:189], v132 offset:0x3200
	ds_read_b64_tr_b16 v[190:191], v132 offset:0x3a00
	s_waitcnt lgkmcnt(6)
	v_mfma_f32_32x32x16_bf16 v[48:63], v[148:151], v[112:115], v[48:63]
	ds_read_b64_tr_b16 v[148:149], v132 offset:0x400
	ds_read_b64_tr_b16 v[150:151], v132 offset:0xc00
	s_waitcnt lgkmcnt(6)
	v_mfma_f32_32x32x16_bf16 v[48:63], v[152:155], v[120:123], v[48:63]
	ds_read_b64_tr_b16 v[152:153], v132 offset:0x1400
	ds_read_b64_tr_b16 v[154:155], v132 offset:0x1c00
	s_waitcnt lgkmcnt(6)
	v_mfma_f32_32x32x16_bf16 v[48:63], v[170:173], v[124:127], v[48:63]
	ds_read_b64_tr_b16 v[170:171], v132 offset:0x2400
	ds_read_b64_tr_b16 v[172:173], v132 offset:0x2c00
	s_waitcnt lgkmcnt(6)
	v_mfma_f32_32x32x16_bf16 v[48:63], v[188:191], v[144:147], v[48:63]
	ds_read_b64_tr_b16 v[188:189], v132 offset:0x3400
	ds_read_b64_tr_b16 v[190:191], v132 offset:0x3c00
	s_waitcnt lgkmcnt(6)
; #define SBAR() __builtin_amdgcn_sched_barrier(0)
; template <int MLA>
; __device__ __forceinline__ void partialSM(f32x16& p0, f32x16& p1, float& m_reg, float& mn, float& alpha) {
;     ...
;   float pmax = p0[0];
; #pragma unroll
;   for (int r = 1; r < 16; ++r) pmax = fmaxf(pmax, p0[r]);
; #pragma unroll
;   for (int r = 0; r < 16; ++r) pmax = fmaxf(pmax, p1[r]);
;   { auto rr = __builtin_amdgcn_permlane32_swap(__float_as_uint(pmax), __float_as_uint(pmax), false, false);
;     pmax = fmaxf(__uint_as_float(rr[0]), __uint_as_float(rr[1])); }
;   if (__builtin_expect(__all(pmax - m_reg <= THR / SCALE), 1)) { mn = m_reg; alpha = 1.f; }
;   else { mn = fmaxf(m_reg, pmax); alpha = __builtin_amdgcn_exp2f((m_reg - mn) * C); m_reg = mn; }
;   float mnC = -mn * C;
; #pragma unroll
;   for (int r = 0; r < 16; ++r) p0[r] = fmaf(p0[r], C, mnC);
; #pragma unroll
;   for (int r = 0; r < 16; ++r) p1[r] = fmaf(p1[r], C, mnC);
; template <int D0> __device__ __forceinline__ void pv_one_t(f32x16& od, int vb, bf16x8 pa0, bf16x8 pa1, bf16x8 pa2, bf16x8 pa3) {
;   const s16x4 l0 = tr_read<v_rd_off(D0, 0, 0)>(vb), h0 = tr_read<v_rd_off(D0, 0, 1)>(vb), l1 = tr_read<v_rd_off(D0, 1, 0)>(vb), h1 = tr_read<v_rd_off(D0, 1, 1)>(vb);
;   const s16x4 l2 = tr_read<v_rd_off(D0, 2, 0)>(vb), h2 = tr_read<v_rd_off(D0, 2, 1)>(vb), l3 = tr_read<v_rd_off(D0, 3, 0)>(vb), h3 = tr_read<v_rd_off(D0, 3, 1)>(vb);
;   asm volatile("s_waitcnt lgkmcnt(0)" ::: "memory"); SBAR();
;     ...
;   od = __builtin_amdgcn_mfma_f32_32x32x16_bf16(PK(l0, h0), pa0, od, 0, 0, 0);
;   od = __builtin_amdgcn_mfma_f32_32x32x16_bf16(PK(l1, h1), pa1, od, 0, 0, 0);
;   od = __builtin_amdgcn_mfma_f32_32x32x16_bf16(PK(l2, h2), pa2, od, 0, 0, 0);
;   od = __builtin_amdgcn_mfma_f32_32x32x16_bf16(PK(l3, h3), pa3, od, 0, 0, 0);
;     ...
; }
	v_mfma_f32_32x32x16_bf16 v[16:31], v[148:151], v[112:115], v[16:31]
	ds_read_b64_tr_b16 v[148:149], v132 offset:0x600
	ds_read_b64_tr_b16 v[150:151], v132 offset:0xe00
	s_waitcnt lgkmcnt(6)
	v_mfma_f32_32x32x16_bf16 v[16:31], v[152:155], v[120:123], v[16:31]
	ds_read_b64_tr_b16 v[152:153], v132 offset:0x1600
	ds_read_b64_tr_b16 v[154:155], v132 offset:0x1e00
	s_waitcnt lgkmcnt(6)
	v_mfma_f32_32x32x16_bf16 v[16:31], v[170:173], v[124:127], v[16:31]
	ds_read_b64_tr_b16 v[170:171], v132 offset:0x2600
	ds_read_b64_tr_b16 v[172:173], v132 offset:0x2e00
	s_waitcnt lgkmcnt(6)
	v_mfma_f32_32x32x16_bf16 v[16:31], v[188:191], v[144:147], v[16:31]
	ds_read_b64_tr_b16 v[188:189], v132 offset:0x3600
	ds_read_b64_tr_b16 v[190:191], v132 offset:0x3e00
	s_waitcnt lgkmcnt(6)
	v_mfma_f32_32x32x16_bf16 v[0:15], v[148:151], v[112:115], v[0:15]
	v_max_f32_e32 v112, v80, v81
	v_max3_f32 v112, v112, v82, v83
	v_max3_f32 v112, v112, v84, v85
	v_max3_f32 v112, v112, v86, v87
	v_max3_f32 v112, v112, v88, v89
	v_max3_f32 v112, v112, v90, v91
	v_max3_f32 v112, v112, v92, v93
	s_waitcnt lgkmcnt(4)
	v_mfma_f32_32x32x16_bf16 v[0:15], v[152:155], v[120:123], v[0:15]
	v_max3_f32 v112, v112, v94, v95
	v_max3_f32 v112, v112, v64, v65
	v_max3_f32 v112, v112, v66, v67
	v_max3_f32 v112, v112, v68, v69
	v_max3_f32 v112, v112, v70, v71
	v_max3_f32 v112, v112, v72, v73
	v_max3_f32 v112, v112, v74, v75
	v_max3_f32 v112, v112, v76, v77
	s_waitcnt lgkmcnt(2)
	v_mfma_f32_32x32x16_bf16 v[0:15], v[170:173], v[124:127], v[0:15]
	v_max3_f32 v112, v112, v78, v79
	v_mov_b32_e32 v113, v112
	s_nop 1
	v_permlane32_swap_b32_e32 v112, v113
	v_max_f32_e32 v112, v112, v113
	v_cmp_nge_f32_e32 vcc, s70, v112
	s_waitcnt lgkmcnt(0)
	v_mfma_f32_32x32x16_bf16 v[0:15], v[188:191], v[144:147], v[0:15]
	s_waitcnt vmcnt(0) lgkmcnt(0)
	s_barrier
	s_cbranch_vccz .Lal_c_d1
	v_max_f32_e32 v242, 0, v112
	v_exp_f32_e64 v116, -v242
	s_nop 0
	v_pk_mul_f32 v[46:47], v[46:47], v[116:117] op_sel_hi:[1,0]
	v_pk_mul_f32 v[44:45], v[44:45], v[116:117] op_sel_hi:[1,0]
	v_pk_mul_f32 v[42:43], v[42:43], v[116:117] op_sel_hi:[1,0]
	v_pk_mul_f32 v[40:41], v[40:41], v[116:117] op_sel_hi:[1,0]
	v_pk_mul_f32 v[38:39], v[38:39], v[116:117] op_sel_hi:[1,0]
	v_pk_mul_f32 v[36:37], v[36:37], v[116:117] op_sel_hi:[1,0]
	v_pk_mul_f32 v[34:35], v[34:35], v[116:117] op_sel_hi:[1,0]
	v_pk_mul_f32 v[32:33], v[32:33], v[116:117] op_sel_hi:[1,0]
	v_pk_mul_f32 v[62:63], v[62:63], v[116:117] op_sel_hi:[1,0]
	v_pk_mul_f32 v[60:61], v[60:61], v[116:117] op_sel_hi:[1,0]
	v_pk_mul_f32 v[58:59], v[58:59], v[116:117] op_sel_hi:[1,0]
	v_pk_mul_f32 v[56:57], v[56:57], v[116:117] op_sel_hi:[1,0]
	v_pk_mul_f32 v[54:55], v[54:55], v[116:117] op_sel_hi:[1,0]
	v_pk_mul_f32 v[52:53], v[52:53], v[116:117] op_sel_hi:[1,0]
	v_pk_mul_f32 v[50:51], v[50:51], v[116:117] op_sel_hi:[1,0]
	v_pk_mul_f32 v[48:49], v[48:49], v[116:117] op_sel_hi:[1,0]
	v_pk_mul_f32 v[30:31], v[30:31], v[116:117] op_sel_hi:[1,0]
	v_pk_mul_f32 v[28:29], v[28:29], v[116:117] op_sel_hi:[1,0]
	v_pk_mul_f32 v[26:27], v[26:27], v[116:117] op_sel_hi:[1,0]
	v_pk_mul_f32 v[24:25], v[24:25], v[116:117] op_sel_hi:[1,0]
	v_pk_mul_f32 v[22:23], v[22:23], v[116:117] op_sel_hi:[1,0]
	v_pk_mul_f32 v[20:21], v[20:21], v[116:117] op_sel_hi:[1,0]
	v_pk_mul_f32 v[18:19], v[18:19], v[116:117] op_sel_hi:[1,0]
	v_pk_mul_f32 v[16:17], v[16:17], v[116:117] op_sel_hi:[1,0]
	v_pk_mul_f32 v[14:15], v[14:15], v[116:117] op_sel_hi:[1,0]
	v_pk_mul_f32 v[12:13], v[12:13], v[116:117] op_sel_hi:[1,0]
	v_pk_mul_f32 v[10:11], v[10:11], v[116:117] op_sel_hi:[1,0]
	v_pk_mul_f32 v[8:9], v[8:9], v[116:117] op_sel_hi:[1,0]
	v_pk_mul_f32 v[6:7], v[6:7], v[116:117] op_sel_hi:[1,0]
	v_pk_mul_f32 v[4:5], v[4:5], v[116:117] op_sel_hi:[1,0]
	v_pk_mul_f32 v[2:3], v[2:3], v[116:117] op_sel_hi:[1,0]
	v_pk_mul_f32 v[0:1], v[0:1], v[116:117] op_sel_hi:[1,0]
	v_sub_f32_e32 v80, v80, v242
	v_sub_f32_e32 v81, v81, v242
	v_sub_f32_e32 v82, v82, v242
	v_sub_f32_e32 v83, v83, v242
	v_sub_f32_e32 v84, v84, v242
	v_sub_f32_e32 v85, v85, v242
	v_sub_f32_e32 v86, v86, v242
	v_sub_f32_e32 v87, v87, v242
	v_sub_f32_e32 v88, v88, v242
	v_sub_f32_e32 v89, v89, v242
	v_sub_f32_e32 v90, v90, v242
	v_sub_f32_e32 v91, v91, v242
	v_sub_f32_e32 v92, v92, v242
	v_sub_f32_e32 v93, v93, v242
	v_sub_f32_e32 v94, v94, v242
	v_sub_f32_e32 v95, v95, v242
	v_sub_f32_e32 v64, v64, v242
	v_sub_f32_e32 v65, v65, v242
	v_sub_f32_e32 v66, v66, v242
	v_sub_f32_e32 v67, v67, v242
	v_sub_f32_e32 v68, v68, v242
	v_sub_f32_e32 v69, v69, v242
	v_sub_f32_e32 v70, v70, v242
	v_sub_f32_e32 v71, v71, v242
	v_sub_f32_e32 v72, v72, v242
	v_sub_f32_e32 v73, v73, v242
	v_sub_f32_e32 v74, v74, v242
	v_sub_f32_e32 v75, v75, v242
	v_sub_f32_e32 v76, v76, v242
	v_sub_f32_e32 v77, v77, v242
	v_sub_f32_e32 v78, v78, v242
	v_sub_f32_e32 v79, v79, v242
	v_sub_f32_e32 v226, v226, v242
	v_sub_f32_e32 v227, v227, v242
	v_sub_f32_e32 v228, v228, v242
	v_sub_f32_e32 v229, v229, v242
	v_sub_f32_e32 v230, v230, v242
	v_sub_f32_e32 v231, v231, v242
	v_sub_f32_e32 v232, v232, v242
	v_sub_f32_e32 v233, v233, v242
	v_sub_f32_e32 v234, v234, v242
	v_sub_f32_e32 v235, v235, v242
	v_sub_f32_e32 v236, v236, v242
	v_sub_f32_e32 v237, v237, v242
	v_sub_f32_e32 v238, v238, v242
	v_sub_f32_e32 v239, v239, v242
	v_sub_f32_e32 v240, v240, v242
	v_sub_f32_e32 v241, v241, v242
	s_branch .LBB0_131

; __device__ __forceinline__ void finishSM(f32x16& p0, f32x16& p1, float alpha, float& l_reg, bf16x8& pa0, bf16x8& pa1, bf16x8& pa2, bf16x8& pa3) {
; #pragma unroll
;   for (int r = 0; r < 16; ++r) p1[r] = __builtin_amdgcn_exp2f(p1[r]);
;   float ps = 0;
; #pragma unroll
;   for (int r = 0; r < 16; ++r) ps += p0[r];
; #pragma unroll
;   for (int r = 0; r < 16; ++r) ps += p1[r];
;   { auto rr = __builtin_amdgcn_permlane32_swap(__float_as_uint(ps), __float_as_uint(ps), false, false);
;     ps = __uint_as_float(rr[0]) + __uint_as_float(rr[1]); }
;   l_reg = l_reg * alpha + ps;
;     ...
;   PK4(p0, 0, pa0); PK4(p0, 8, pa1); PK4(p1, 0, pa2); PK4(p1, 8, pa3);
; template <int BUFOFF>
; __device__ __forceinline__ void qkt_diff(f32x16& p0, f32x16& p1, const int* ka, const bf16x8* qr) {
;   typedef __attribute__((address_space(3))) const bf16x8* lp;
;   p0 = f32x16{}; p1 = f32x16{};
; #pragma unroll
;   for (int d0 = 0; d0 < 4; ++d0) {
;     const int a = ka[d0] + BUFOFF;
;     const bf16x8 b0 = *(lp)(a), b1 = *(lp)(a + 8192);
;     p0 = __builtin_amdgcn_mfma_f32_32x32x16_bf16(b0, qr[d0], p0, 0, 0, 0);
;     p1 = __builtin_amdgcn_mfma_f32_32x32x16_bf16(b1, qr[d0], p1, 0, 0, 0);
;   }
; }
.LBB0_131:
	v_exp_f32_e32 v125, v64
	v_exp_f32_e32 v126, v65
	v_exp_f32_e32 v127, v66
	v_exp_f32_e32 v128, v67
	v_exp_f32_e32 v129, v68
	v_exp_f32_e32 v143, v69
	v_exp_f32_e32 v144, v70
	v_exp_f32_e32 v145, v71
	v_exp_f32_e32 v146, v72
	v_exp_f32_e32 v147, v73
	v_exp_f32_e32 v148, v74
	v_exp_f32_e32 v149, v75
	v_exp_f32_e32 v150, v76
	v_exp_f32_e32 v151, v80
	v_exp_f32_e32 v152, v81
	v_exp_f32_e32 v153, v82
	v_exp_f32_e32 v154, v83
	v_exp_f32_e32 v155, v84
	v_exp_f32_e32 v156, v85
	v_exp_f32_e32 v158, v86
	v_exp_f32_e32 v159, v87
	v_exp_f32_e32 v162, v88
	v_exp_f32_e32 v167, v89
	v_exp_f32_e32 v169, v90
	v_exp_f32_e32 v170, v91
	v_exp_f32_e32 v171, v92
	v_exp_f32_e32 v172, v93
	v_exp_f32_e32 v173, v94
	v_exp_f32_e32 v188, v95
	v_exp_f32_e32 v189, v77
	v_exp_f32_e32 v190, v78
	v_exp_f32_e32 v124, v79
	ds_read_b128 v[64:67], v138
	ds_read_b128 v[68:71], v138 offset:8192
	ds_read_b128 v[112:115], v141
	ds_read_b128 v[120:123], v141 offset:8192
	v_mov_b32_e32 v191, v125
	s_waitcnt lgkmcnt(0)
	v_mfma_f32_32x32x16_bf16 v[80:95], v[64:67], v[108:111], v[226:241]
	v_mfma_f32_32x32x16_bf16 v[64:79], v[68:71], v[108:111], v[226:241]
	v_mov_b32_e32 v192, v124
	v_mfma_f32_32x32x16_bf16 v[80:95], v[112:115], v[104:107], v[80:95]
	v_mfma_f32_32x32x16_bf16 v[64:79], v[120:123], v[104:107], v[64:79]
	ds_read_b128 v[112:115], v140
	ds_read_b128 v[120:123], v140 offset:8192
	s_waitcnt lgkmcnt(0)
	v_mfma_f32_32x32x16_bf16 v[80:95], v[112:115], v[100:103], v[80:95]
	v_mfma_f32_32x32x16_bf16 v[64:79], v[120:123], v[100:103], v[64:79]
	ds_read_b128 v[112:115], v139
	ds_read_b128 v[120:123], v139 offset:8192
	s_waitcnt lgkmcnt(0)
	v_mfma_f32_32x32x16_bf16 v[80:95], v[112:115], v[96:99], v[80:95]
	v_add_f32_e32 v112, v162, v151
	v_add_f32_e32 v243, v167, v152
	v_add_f32_e32 v244, v169, v153
	v_add_f32_e32 v245, v170, v154
	v_add_f32_e32 v246, v171, v155
	v_add_f32_e32 v247, v172, v156
	v_add_f32_e32 v251, v173, v158
	v_add_f32_e32 v252, v188, v159
	v_add_f32_e32 v112, v191, v112
	v_add_f32_e32 v243, v126, v243
	v_add_f32_e32 v244, v127, v244
	v_add_f32_e32 v245, v128, v245
	v_add_f32_e32 v246, v129, v246
	v_add_f32_e32 v247, v143, v247
	v_add_f32_e32 v251, v144, v251
	v_add_f32_e32 v252, v145, v252
	v_add_f32_e32 v112, v146, v112
	v_add_f32_e32 v243, v147, v243
	v_mfma_f32_32x32x16_bf16 v[64:79], v[120:123], v[96:99], v[64:79]
	v_add_f32_e32 v244, v148, v244
	v_add_f32_e32 v245, v149, v245
	v_add_f32_e32 v246, v150, v246
	v_add_f32_e32 v247, v189, v247
	v_add_f32_e32 v251, v190, v251
	v_add_f32_e32 v252, v192, v252
	v_add_f32_e32 v112, v112, v243
	v_add_f32_e32 v244, v244, v245
	v_add_f32_e32 v246, v246, v247
	v_add_f32_e32 v251, v251, v252
	v_add_f32_e32 v112, v112, v244
	v_add_f32_e32 v246, v246, v251
	v_add_f32_e32 v120, v112, v246
	v_mov_b32_e32 v121, v120
	v_cvt_pk_bf16_f32 v112, v151, v152
	v_cvt_pk_bf16_f32 v113, v153, v154
	v_cvt_pk_bf16_f32 v114, v155, v156
	v_cvt_pk_bf16_f32 v115, v158, v159
	s_nop 1
	v_permlane32_swap_b32_e32 v120, v121
	v_cvt_pk_bf16_f32 v122, v162, v167
	v_cvt_pk_bf16_f32 v123, v169, v170
	v_cvt_pk_bf16_f32 v124, v171, v172
	v_cvt_pk_bf16_f32 v125, v173, v188
	v_cvt_pk_bf16_f32 v126, v191, v126
	v_cvt_pk_bf16_f32 v127, v127, v128
	v_cvt_pk_bf16_f32 v128, v129, v143
	v_cvt_pk_bf16_f32 v129, v144, v145
	v_cvt_pk_bf16_f32 v144, v146, v147
	v_cvt_pk_bf16_f32 v145, v148, v149
	v_cvt_pk_bf16_f32 v146, v150, v189
	v_cvt_pk_bf16_f32 v147, v190, v192
	s_nop 0
	s_add_u32 s4, s14, 0x20000
	s_addc_u32 s5, s15, 0
	s_add_u32 s56, s14, 0x2020000
	s_mov_b32 m0, s16
	s_addc_u32 s57, s15, 0
	s_add_i32 s55, s42, s55
	s_nop 0
	global_load_lds_dwordx4 v134, s[4:5]
	s_mov_b32 m0, s17
	s_nop 0
	global_load_lds_dwordx4 v135, s[4:5]
	s_mov_b32 m0, s55
	s_nop 0
	global_load_lds_dwordx4 v136, s[56:57]
	s_add_i32 m0, s55, 0x2000
	s_nop 0
	global_load_lds_dwordx4 v137, s[56:57]
	v_lshl_add_u32 v143, s54, 14, v133
	ds_read_b64_tr_b16 v[148:149], v143 offset:0
	ds_read_b64_tr_b16 v[150:151], v143 offset:0x800
	ds_read_b64_tr_b16 v[152:153], v143 offset:0x1000
	ds_read_b64_tr_b16 v[154:155], v143 offset:0x1800
	ds_read_b64_tr_b16 v[170:171], v143 offset:0x2000
	ds_read_b64_tr_b16 v[172:173], v143 offset:0x2800
	ds_read_b64_tr_b16 v[188:189], v143 offset:0x3000
	ds_read_b64_tr_b16 v[190:191], v143 offset:0x3800
	s_nop 0
	s_waitcnt lgkmcnt(6)
	v_mfma_f32_32x32x16_bf16 v[32:47], v[148:151], v[112:115], v[32:47]
	ds_read_b64_tr_b16 v[148:149], v143 offset:0x200
	ds_read_b64_tr_b16 v[150:151], v143 offset:0xa00
	s_waitcnt lgkmcnt(6)
	v_mfma_f32_32x32x16_bf16 v[32:47], v[152:155], v[122:125], v[32:47]
	ds_read_b64_tr_b16 v[152:153], v143 offset:0x1200
	ds_read_b64_tr_b16 v[154:155], v143 offset:0x1a00
	s_waitcnt lgkmcnt(6)
	v_mfma_f32_32x32x16_bf16 v[32:47], v[170:173], v[126:129], v[32:47]
	ds_read_b64_tr_b16 v[170:171], v143 offset:0x2200
	ds_read_b64_tr_b16 v[172:173], v143 offset:0x2a00
	s_waitcnt lgkmcnt(6)
	v_mfma_f32_32x32x16_bf16 v[32:47], v[188:191], v[144:147], v[32:47]
	ds_read_b64_tr_b16 v[188:189], v143 offset:0x3200
	ds_read_b64_tr_b16 v[190:191], v143 offset:0x3a00
	s_waitcnt lgkmcnt(6)
	v_mfma_f32_32x32x16_bf16 v[48:63], v[148:151], v[112:115], v[48:63]
	ds_read_b64_tr_b16 v[148:149], v143 offset:0x400
	ds_read_b64_tr_b16 v[150:151], v143 offset:0xc00
	s_waitcnt lgkmcnt(6)
	v_mfma_f32_32x32x16_bf16 v[48:63], v[152:155], v[122:125], v[48:63]
	ds_read_b64_tr_b16 v[152:153], v143 offset:0x1400
	ds_read_b64_tr_b16 v[154:155], v143 offset:0x1c00
	s_waitcnt lgkmcnt(6)
	v_mfma_f32_32x32x16_bf16 v[48:63], v[170:173], v[126:129], v[48:63]
	ds_read_b64_tr_b16 v[170:171], v143 offset:0x2400
	ds_read_b64_tr_b16 v[172:173], v143 offset:0x2c00
	s_waitcnt lgkmcnt(6)
; #define SBAR() __builtin_amdgcn_sched_barrier(0)
; template <int MLA>
; __device__ __forceinline__ void partialSM(f32x16& p0, f32x16& p1, float& m_reg, float& mn, float& alpha) {
;     ...
;   float pmax = p0[0];
; #pragma unroll
;   for (int r = 1; r < 16; ++r) pmax = fmaxf(pmax, p0[r]);
; #pragma unroll
;   for (int r = 0; r < 16; ++r) pmax = fmaxf(pmax, p1[r]);
;   { auto rr = __builtin_amdgcn_permlane32_swap(__float_as_uint(pmax), __float_as_uint(pmax), false, false);
;     pmax = fmaxf(__uint_as_float(rr[0]), __uint_as_float(rr[1])); }
;   if (__builtin_expect(__all(pmax - m_reg <= THR / SCALE), 1)) { mn = m_reg; alpha = 1.f; }
;   else { mn = fmaxf(m_reg, pmax); alpha = __builtin_amdgcn_exp2f((m_reg - mn) * C); m_reg = mn; }
;   float mnC = -mn * C;
; #pragma unroll
;   for (int r = 0; r < 16; ++r) p0[r] = fmaf(p0[r], C, mnC);
; #pragma unroll
;   for (int r = 0; r < 16; ++r) p1[r] = fmaf(p1[r], C, mnC);
; template <int D0> __device__ __forceinline__ void pv_one_t(f32x16& od, int vb, bf16x8 pa0, bf16x8 pa1, bf16x8 pa2, bf16x8 pa3) {
;   const s16x4 l0 = tr_read<v_rd_off(D0, 0, 0)>(vb), h0 = tr_read<v_rd_off(D0, 0, 1)>(vb), l1 = tr_read<v_rd_off(D0, 1, 0)>(vb), h1 = tr_read<v_rd_off(D0, 1, 1)>(vb);
;   const s16x4 l2 = tr_read<v_rd_off(D0, 2, 0)>(vb), h2 = tr_read<v_rd_off(D0, 2, 1)>(vb), l3 = tr_read<v_rd_off(D0, 3, 0)>(vb), h3 = tr_read<v_rd_off(D0, 3, 1)>(vb);
;   asm volatile("s_waitcnt lgkmcnt(0)" ::: "memory"); SBAR();
;     ...
;   od = __builtin_amdgcn_mfma_f32_32x32x16_bf16(PK(l0, h0), pa0, od, 0, 0, 0);
;   od = __builtin_amdgcn_mfma_f32_32x32x16_bf16(PK(l1, h1), pa1, od, 0, 0, 0);
;   od = __builtin_amdgcn_mfma_f32_32x32x16_bf16(PK(l2, h2), pa2, od, 0, 0, 0);
;   od = __builtin_amdgcn_mfma_f32_32x32x16_bf16(PK(l3, h3), pa3, od, 0, 0, 0);
;     ...
; }
	v_mfma_f32_32x32x16_bf16 v[48:63], v[188:191], v[144:147], v[48:63]
	ds_read_b64_tr_b16 v[188:189], v143 offset:0x3400
	ds_read_b64_tr_b16 v[190:191], v143 offset:0x3c00
	s_waitcnt lgkmcnt(6)
	v_mfma_f32_32x32x16_bf16 v[16:31], v[148:151], v[112:115], v[16:31]
	ds_read_b64_tr_b16 v[148:149], v143 offset:0x600
	ds_read_b64_tr_b16 v[150:151], v143 offset:0xe00
	s_waitcnt lgkmcnt(6)
	v_mfma_f32_32x32x16_bf16 v[16:31], v[152:155], v[122:125], v[16:31]
	ds_read_b64_tr_b16 v[152:153], v143 offset:0x1600
	ds_read_b64_tr_b16 v[154:155], v143 offset:0x1e00
	s_waitcnt lgkmcnt(6)
	v_mfma_f32_32x32x16_bf16 v[16:31], v[170:173], v[126:129], v[16:31]
	ds_read_b64_tr_b16 v[170:171], v143 offset:0x2600
	ds_read_b64_tr_b16 v[172:173], v143 offset:0x2e00
	s_waitcnt lgkmcnt(6)
	v_mfma_f32_32x32x16_bf16 v[16:31], v[188:191], v[144:147], v[16:31]
	ds_read_b64_tr_b16 v[188:189], v143 offset:0x3600
	ds_read_b64_tr_b16 v[190:191], v143 offset:0x3e00
	s_waitcnt lgkmcnt(6)
	v_mfma_f32_32x32x16_bf16 v[0:15], v[148:151], v[112:115], v[0:15]
	v_max_f32_e32 v112, v80, v81
	v_max3_f32 v112, v112, v82, v83
	v_max3_f32 v112, v112, v84, v85
	v_max3_f32 v112, v112, v86, v87
	v_max3_f32 v112, v112, v88, v89
	v_max3_f32 v112, v112, v90, v91
	v_max3_f32 v112, v112, v92, v93
	s_waitcnt lgkmcnt(4)
	v_mfma_f32_32x32x16_bf16 v[0:15], v[152:155], v[122:125], v[0:15]
	v_max3_f32 v112, v112, v94, v95
	v_max3_f32 v112, v112, v64, v65
	v_max3_f32 v112, v112, v66, v67
	v_max3_f32 v112, v112, v68, v69
	v_max3_f32 v112, v112, v70, v71
	v_max3_f32 v112, v112, v72, v73
	v_max3_f32 v112, v112, v74, v75
	v_max3_f32 v112, v112, v76, v77
	s_waitcnt lgkmcnt(2)
	v_mfma_f32_32x32x16_bf16 v[0:15], v[170:173], v[126:129], v[0:15]
	v_max3_f32 v112, v112, v78, v79
	v_mov_b32_e32 v113, v112
	s_nop 1
	v_permlane32_swap_b32_e32 v112, v113
	v_max_f32_e32 v112, v112, v113
	v_cmp_nge_f32_e32 vcc, s70, v112
	s_waitcnt lgkmcnt(0)
	v_mfma_f32_32x32x16_bf16 v[0:15], v[188:191], v[144:147], v[0:15]
	s_waitcnt vmcnt(0) lgkmcnt(0)
	s_barrier
	s_cbranch_vccz .Lal_c_d2
	v_max_f32_e32 v242, 0, v112
	v_exp_f32_e64 v112, -v242
	s_nop 0
	v_pk_mul_f32 v[46:47], v[46:47], v[112:113] op_sel_hi:[1,0]
	v_pk_mul_f32 v[44:45], v[44:45], v[112:113] op_sel_hi:[1,0]
	v_pk_mul_f32 v[42:43], v[42:43], v[112:113] op_sel_hi:[1,0]
	v_pk_mul_f32 v[40:41], v[40:41], v[112:113] op_sel_hi:[1,0]
	v_pk_mul_f32 v[38:39], v[38:39], v[112:113] op_sel_hi:[1,0]
	v_pk_mul_f32 v[36:37], v[36:37], v[112:113] op_sel_hi:[1,0]
	v_pk_mul_f32 v[34:35], v[34:35], v[112:113] op_sel_hi:[1,0]
	v_pk_mul_f32 v[32:33], v[32:33], v[112:113] op_sel_hi:[1,0]
	v_pk_mul_f32 v[62:63], v[62:63], v[112:113] op_sel_hi:[1,0]
	v_pk_mul_f32 v[60:61], v[60:61], v[112:113] op_sel_hi:[1,0]
	v_pk_mul_f32 v[58:59], v[58:59], v[112:113] op_sel_hi:[1,0]
	v_pk_mul_f32 v[56:57], v[56:57], v[112:113] op_sel_hi:[1,0]
	v_pk_mul_f32 v[54:55], v[54:55], v[112:113] op_sel_hi:[1,0]
	v_pk_mul_f32 v[52:53], v[52:53], v[112:113] op_sel_hi:[1,0]
	v_pk_mul_f32 v[50:51], v[50:51], v[112:113] op_sel_hi:[1,0]
	v_pk_mul_f32 v[48:49], v[48:49], v[112:113] op_sel_hi:[1,0]
	v_pk_mul_f32 v[30:31], v[30:31], v[112:113] op_sel_hi:[1,0]
	v_pk_mul_f32 v[28:29], v[28:29], v[112:113] op_sel_hi:[1,0]
	v_pk_mul_f32 v[26:27], v[26:27], v[112:113] op_sel_hi:[1,0]
	v_pk_mul_f32 v[24:25], v[24:25], v[112:113] op_sel_hi:[1,0]
	v_pk_mul_f32 v[22:23], v[22:23], v[112:113] op_sel_hi:[1,0]
	v_pk_mul_f32 v[20:21], v[20:21], v[112:113] op_sel_hi:[1,0]
	v_pk_mul_f32 v[18:19], v[18:19], v[112:113] op_sel_hi:[1,0]
	v_pk_mul_f32 v[16:17], v[16:17], v[112:113] op_sel_hi:[1,0]
	v_pk_mul_f32 v[14:15], v[14:15], v[112:113] op_sel_hi:[1,0]
	v_pk_mul_f32 v[12:13], v[12:13], v[112:113] op_sel_hi:[1,0]
	v_pk_mul_f32 v[10:11], v[10:11], v[112:113] op_sel_hi:[1,0]
	v_pk_mul_f32 v[8:9], v[8:9], v[112:113] op_sel_hi:[1,0]
	v_pk_mul_f32 v[6:7], v[6:7], v[112:113] op_sel_hi:[1,0]
	v_pk_mul_f32 v[4:5], v[4:5], v[112:113] op_sel_hi:[1,0]
	v_pk_mul_f32 v[2:3], v[2:3], v[112:113] op_sel_hi:[1,0]
	v_pk_mul_f32 v[0:1], v[0:1], v[112:113] op_sel_hi:[1,0]
	v_sub_f32_e32 v80, v80, v242
	v_sub_f32_e32 v81, v81, v242
	v_sub_f32_e32 v82, v82, v242
	v_sub_f32_e32 v83, v83, v242
	v_sub_f32_e32 v84, v84, v242
	v_sub_f32_e32 v85, v85, v242
	v_sub_f32_e32 v86, v86, v242
	v_sub_f32_e32 v87, v87, v242
	v_sub_f32_e32 v88, v88, v242
	v_sub_f32_e32 v89, v89, v242
	v_sub_f32_e32 v90, v90, v242
	v_sub_f32_e32 v91, v91, v242
	v_sub_f32_e32 v92, v92, v242
	v_sub_f32_e32 v93, v93, v242
	v_sub_f32_e32 v94, v94, v242
	v_sub_f32_e32 v95, v95, v242
	v_sub_f32_e32 v64, v64, v242
	v_sub_f32_e32 v65, v65, v242
	v_sub_f32_e32 v66, v66, v242
	v_sub_f32_e32 v67, v67, v242
	v_sub_f32_e32 v68, v68, v242
	v_sub_f32_e32 v69, v69, v242
	v_sub_f32_e32 v70, v70, v242
	v_sub_f32_e32 v71, v71, v242
	v_sub_f32_e32 v72, v72, v242
	v_sub_f32_e32 v73, v73, v242
	v_sub_f32_e32 v74, v74, v242
	v_sub_f32_e32 v75, v75, v242
	v_sub_f32_e32 v76, v76, v242
	v_sub_f32_e32 v77, v77, v242
	v_sub_f32_e32 v78, v78, v242
	v_sub_f32_e32 v79, v79, v242
	v_sub_f32_e32 v226, v226, v242
	v_sub_f32_e32 v227, v227, v242
	v_sub_f32_e32 v228, v228, v242
	v_sub_f32_e32 v229, v229, v242
	v_sub_f32_e32 v230, v230, v242
	v_sub_f32_e32 v231, v231, v242
	v_sub_f32_e32 v232, v232, v242
	v_sub_f32_e32 v233, v233, v242
	v_sub_f32_e32 v234, v234, v242
	v_sub_f32_e32 v235, v235, v242
	v_sub_f32_e32 v236, v236, v242
	v_sub_f32_e32 v237, v237, v242
	v_sub_f32_e32 v238, v238, v242
	v_sub_f32_e32 v239, v239, v242
	v_sub_f32_e32 v240, v240, v242
	v_sub_f32_e32 v241, v241, v242
	s_branch .LBB0_133
